# v69 + ssd_s3: per-head hprev fragments staged via LDS-DMA into the dead Bs region (each wave fetches 2 of 16 fragments, next head prefetched, double-buffered) instead of every wave loading all 16 from
# speedup vs baseline: 1.0209x; 1.0209x over previous
; __device__ __forceinline__ void ssd_s3_unit(const Params& p, int unit, unsigned char* ldsb) {
;     ...
;     const int lrow = wave * 16 + l15;
;     for (int hh = 0; hh < 4; ++hh) {
;         const int h = g * 4 + hh;
;         const bfu* XT = XT4 + hh * 64 * 136;
;         const float csl = csb[hh * 128 + lrow];
;         f32x4 acc[4];
; #pragma unroll
;         for (int mt = 0; mt < 4; ++mt) acc[mt] = (f32x4){0.f, 0.f, 0.f, 0.f};
;         const bfu* hp = (const bfu*)(p.ws + WS_HPREV) + ((size_t)((b * 32 + c) * 16 + h) * 64) * 128;
;         bf16x8 hf[16];
; #pragma unroll
;         for (int i = 0; i < 16; ++i) hf[i] = ld8g(hp + (size_t)((i & 3) * 16 + l15) * 128 + (i >> 2) * 32 + quad * 8);
.LBB0_541:
	s_lshr_b32 s8, s87, 2
	s_and_b32 s8, s8, 31
	s_lshl_b32 s9, s8, 4
	s_and_b32 s20, s86, 3
	s_lshl_b32 s6, s6, 9
	s_load_dwordx2 s[90:91], s[90:91], 0x58
	s_lshl_b32 s96, s20, 2
	s_lshl_b32 s11, s8, 7
	s_lshl_b32 s8, s20, 8
	s_or_b32 s6, s6, s9
	v_or_b32_e32 v32, s8, v180
	v_or_b32_e32 v35, s8, v64
	v_or_b32_e32 v36, s8, v60
	v_or_b32_e32 v37, s8, v56
	s_or_b32 s8, s6, s96
	s_ashr_i32 s9, s8, 31
	s_lshl_b32 s10, s20, 4
	s_lshl_b64 s[8:9], s[8:9], 14
	v_lshlrev_b32_e32 v34, 1, v32
	v_lshl_or_b32 v32, v174, 8, v176
	s_waitcnt lgkmcnt(0)
	s_add_u32 s96, s90, s10
	v_or_b32_e32 v98, s8, v32
	s_addc_u32 s6, s91, 0
	s_add_i32 s8, vcc_hi, s11
	s_add_i32 s8, s8, s7
	v_add_u32_e32 v32, s8, v174
	v_ashrrev_i32_e32 v33, 31, v32
	s_movk_i32 s7, 0x3000
	v_mov_b32_e32 v99, s9
	v_lshlrev_b64 v[100:101], 11, v[32:33]
	s_andn2_b32 vcc_lo, vcc_lo, 63
	v_mad_i64_i32 v[102:103], s[8:9], v32, s7, 0
	v_lshlrev_b64 v[110:111], 12, v[32:33]
	v_cmp_gt_u32_e64 s[20:21], v180, v48
	v_cmp_lt_u32_e64 s[22:23], v180, v48
	v_cmp_gt_u32_e64 s[24:25], v55, v48
	v_cmp_gt_u32_e64 s[26:27], v54, v48
	v_cmp_gt_u32_e64 s[28:29], v57, v48
	v_cmp_gt_u32_e64 s[30:31], v56, v48
	v_cmp_gt_u32_e64 s[34:35], v59, v48
	v_cmp_gt_u32_e64 s[36:37], v58, v48
	v_cmp_gt_u32_e64 s[38:39], v61, v48
	v_cmp_gt_u32_e64 s[40:41], v60, v48
	v_cmp_gt_u32_e64 s[42:43], v63, v48
	v_cmp_gt_u32_e64 s[44:45], v62, v48
	v_cmp_gt_u32_e64 s[46:47], v65, v48
	v_cmp_gt_u32_e64 s[48:49], v64, v48
	v_cmp_gt_u32_e64 s[50:51], v67, v48
	v_cmp_gt_u32_e64 s[52:53], v66, v48
	v_cmp_gt_u32_e64 s[54:55], v69, v48
	v_cmp_gt_u32_e64 s[56:57], v68, v48
	v_cmp_gt_u32_e64 s[58:59], v71, v48
	v_cmp_gt_u32_e64 s[60:61], v70, v48
	v_cmp_gt_u32_e64 s[62:63], v73, v48
	v_cmp_gt_u32_e64 s[64:65], v72, v48
	v_cmp_gt_u32_e64 s[66:67], v75, v48
	v_cmp_gt_u32_e64 s[68:69], v74, v48
	v_cmp_gt_u32_e64 s[70:71], v77, v48
	v_cmp_gt_u32_e64 s[72:73], v76, v48
	v_cmp_gt_u32_e64 s[74:75], v79, v48
	v_cmp_gt_u32_e64 s[76:77], v78, v48
	v_cmp_gt_u32_e64 s[78:79], v81, v48
	v_cmp_gt_u32_e64 s[80:81], v80, v48
	v_cmp_gt_u32_e64 s[82:83], v83, v48
	v_cmp_gt_u32_e64 s[84:85], v82, v48
	v_or_b32_e32 v100, v100, v34
	v_add_u32_e32 v87, vcc_lo, v154
	v_lshl_or_b32 v104, v35, 1, v102
	v_mov_b32_e32 v105, v103
	v_lshl_or_b32 v106, v36, 1, v102
	v_mov_b32_e32 v107, v103
	v_lshl_or_b32 v108, v37, 1, v102
	v_mov_b32_e32 v109, v103
	v_or_b32_e32 v110, v110, v34
	v_or_b32_e32 v102, v102, v34
	s_mov_b64 s[90:91], 0
	v_mov_b32_e32 v89, v176
	v_mov_b32_e32 v91, v153
	v_mov_b32_e32 v93, v152
	v_mov_b32_e32 v95, v151
	v_mov_b32_e32 v97, v150
	v_mov_b32_e32 v163, v149
	v_mov_b32_e32 v164, v148
	v_mov_b32_e32 v165, v147
	v_mov_b32_e32 v166, v146
	v_mov_b32_e32 v167, v145
	v_mov_b32_e32 v168, v144
	v_mov_b32_e32 v169, v143
	v_mov_b32_e32 v170, v142
	v_mov_b32_e32 v171, v141
	v_mov_b32_e32 v178, v140
	v_mov_b32_e32 v181, v139
	v_mov_b32_e32 v182, v138
	v_mov_b32_e32 v183, v137
	v_mov_b32_e32 v184, v136
	v_mov_b32_e32 v185, v135
	v_mov_b32_e32 v186, v134
	v_mov_b32_e32 v187, v133
	v_mov_b32_e32 v188, v132
	v_mov_b32_e32 v189, v131
	v_mov_b32_e32 v190, v130
	v_mov_b32_e32 v191, v129
	v_mov_b32_e32 v192, v128
	v_mov_b32_e32 v193, v127
	v_mov_b32_e32 v197, v126
	v_mov_b32_e32 v198, v125
	v_mov_b32_e32 v199, v124
	v_mov_b32_e32 v200, v123
	v_mov_b32_e32 v201, v122
	v_add_u32_e32 v202, 0x12100, v122
	s_barrier
	s_lshr_b32 s10, vcc_lo, 7
	s_lshl_b32 s10, s10, 12
	s_and_b32 s11, vcc_lo, 64
	s_lshl_b32 s11, s11, 1
	s_add_i32 s10, s10, s11
	s_add_i32 s10, s10, 0x20a00000
	s_mov_b32 s11, 0
	s_lshl_b32 s32, vcc_lo, 5
	v_lshl_add_u64 v[254:255], s[88:89], 0, v[98:99]
	v_mbcnt_lo_u32_b32 v253, -1, 0
	v_lshl_add_u64 v[254:255], v[254:255], 0, s[10:11]
	v_mbcnt_hi_u32_b32 v253, -1, v253
	v_lshlrev_b32_e32 v253, 4, v253
	v_add_u32_e32 v253, 0x8800, v253
	s_add_i32 s10, s32, 0x8800
	s_mov_b32 m0, s10
	s_nop 0
	global_load_lds_dwordx4 v[254:255], off
	s_add_i32 s10, s10, 0x3c0
	s_mov_b32 m0, s10
	s_nop 0
	global_load_lds_dwordx4 v[254:255], off offset:64
	s_xor_b32 s32, s32, 0x4000
	s_mov_b64 s[10:11], 0x4000
	v_lshl_add_u64 v[254:255], v[254:255], 0, s[10:11]
	s_waitcnt vmcnt(0)
	s_branch .LBB0_543
.LBB0_542:
	s_waitcnt vmcnt(0)
	v_lshl_add_u64 v[50:51], s[88:89], 0, v[110:111]
	v_add_co_u32_e32 v50, vcc, 0x16800000, v50
	v_lshl_add_u64 v[206:207], s[88:89], 0, v[102:103]
	s_nop 0
	v_addc_co_u32_e32 v51, vcc, 0, v51, vcc
	v_add_co_u32_e32 v206, vcc, 0x4301000, v206
	v_mov_b64_e32 v[204:205], v[224:225]
	s_nop 0
	v_addc_co_u32_e32 v207, vcc, 0, v207, vcc
	v_mov_b64_e32 v[206:207], v[226:227]
	s_add_u32 s8, s96, s90
	s_addc_u32 s9, s6, s91
	v_mov_b32_e32 v48, v240
	s_mov_b32 s7, 0x22b00000
	s_add_u32 s90, s90, 4
	s_addc_u32 s91, s91, 0
	s_mov_b64 s[8:9], 0x4000
	v_lshl_add_u64 v[98:99], v[98:99], 0, s[8:9]
	v_lshl_add_u64 v[254:255], v[254:255], 0, s[8:9]
	v_xor_b32_e32 v253, 0x4000, v253
	v_add_u32_e32 v202, 0x4400, v202
	v_add_u32_e32 v201, 0x4400, v201
	v_add_u32_e32 v200, 0x4400, v200
	v_add_u32_e32 v199, 0x200, v199
	v_add_u32_e32 v198, 0x200, v198
	v_add_u32_e32 v197, 0x200, v197
	v_add_u32_e32 v193, 0x200, v193
	v_add_u32_e32 v192, 0x200, v192
	v_add_u32_e32 v191, 0x200, v191
	v_add_u32_e32 v190, 0x200, v190
	v_add_u32_e32 v189, 0x200, v189
	v_add_u32_e32 v188, 0x200, v188
	v_add_u32_e32 v187, 0x200, v187
	v_add_u32_e32 v186, 0x200, v186
	v_add_u32_e32 v185, 0x200, v185
	v_add_u32_e32 v184, 0x200, v184
	v_add_u32_e32 v183, 0x200, v183
	v_add_u32_e32 v182, 0x200, v182
	v_add_u32_e32 v181, 0x200, v181
	v_add_u32_e32 v178, 0x200, v178
	v_add_u32_e32 v171, 0x200, v171
	v_add_u32_e32 v170, 0x200, v170
	v_add_u32_e32 v169, 0x200, v169
	v_add_u32_e32 v168, 0x200, v168
; __device__ __forceinline__ unsigned pk2(float lo, float hi) { f32x2_t v = {lo, hi}; bf16x2_t b = __builtin_convertvector(v, bf16x2_t); return __builtin_bit_cast(unsigned, b); }
; __device__ __forceinline__ float bflo(unsigned u) { return __uint_as_float(u << 16); }
; __device__ __forceinline__ float bfhi(unsigned u) { return __uint_as_float(u & 0xffff0000u); }
; __device__ __forceinline__ float silu_f(float x) { return x * __builtin_amdgcn_rcpf(1.f + __builtin_amdgcn_exp2f(x * -1.4426950408889634f)); }
; __device__ __forceinline__ void ssd_s3_unit(const Params& p, int unit, unsigned char* ldsb) {
;     ...
;         const float dsk = p.d_skip[h];
;         const size_t row = (size_t)(row0 + lrow);
;         bfu* yg = (bfu*)(p.ws + WS_YG);
; #pragma unroll
;         for (int mt = 0; mt < 4; ++mt) {
;             const int pc = h * 64 + mt * 16 + quad * 4;
;             const uint2 xu = *(const uint2*)(xbc + row * 2048 + pc);
;             const uint2 zu = *(const uint2*)(proj + row * NPROJ + 3072 + pc);
;             const float y0 = (acc[mt][0] + dsk * bflo(xu.x)) * silu_f(bflo(zu.x)), y1 = (acc[mt][1] + dsk * bfhi(xu.x)) * silu_f(bfhi(zu.x));
;             const float y2 = (acc[mt][2] + dsk * bflo(xu.y)) * silu_f(bflo(zu.y)), y3 = (acc[mt][3] + dsk * bfhi(xu.y)) * silu_f(bfhi(zu.y));
;             uint2 o; o.x = pk2(y0, y1); o.y = pk2(y2, y3);
;             *(uint2*)(yg + row * 1024 + pc) = o;
;         }
	v_add_u32_e32 v167, 0x200, v167
	v_add_u32_e32 v166, 0x200, v166
	v_add_u32_e32 v165, 0x200, v165
	v_add_u32_e32 v164, 0x200, v164
	v_add_u32_e32 v163, 0x200, v163
	v_add_u32_e32 v97, 0x200, v97
	v_add_u32_e32 v95, 0x200, v95
	v_add_u32_e32 v93, 0x200, v93
	v_add_u32_e32 v91, 0x200, v91
	v_add_u32_e32 v89, 0x200, v89
	v_add_u32_e32 v87, 0x200, v87
	v_lshl_add_u64 v[110:111], v[110:111], 0, s[4:5]
	v_lshl_add_u64 v[102:103], v[102:103], 0, s[4:5]
	s_cmp_lg_u32 s90, 16
	v_lshlrev_b32_e32 v208, 16, v204
	v_and_b32_e32 v209, 0xffff0000, v204
	v_lshlrev_b32_e32 v204, 16, v205
	v_lshlrev_b32_e32 v210, 16, v206
	v_mul_f32_e32 v49, 0xbfb8aa3b, v210
	v_exp_f32_e32 v49, v49
	v_and_b32_e32 v211, 0xffff0000, v206
	v_lshlrev_b32_e32 v206, 16, v207
	v_and_b32_e32 v205, 0xffff0000, v205
	v_add_f32_e32 v49, 1.0, v49
	v_rcp_f32_e32 v212, v49
	v_pk_fma_f32 v[44:45], v[48:49], v[208:209], v[44:45] op_sel_hi:[0,1,1]
	v_mul_f32_e32 v49, 0xbfb8aa3b, v211
	v_exp_f32_e32 v49, v49
	v_and_b32_e32 v207, 0xffff0000, v207
	v_add_f32_e32 v49, 1.0, v49
	v_rcp_f32_e32 v213, v49
	v_mul_f32_e32 v49, 0xbfb8aa3b, v206
	v_exp_f32_e32 v49, v49
	v_pk_mul_f32 v[208:209], v[212:213], v[210:211]
	s_nop 0
	v_pk_mul_f32 v[44:45], v[44:45], v[208:209]
	v_add_f32_e32 v49, 1.0, v49
	v_rcp_f32_e32 v208, v49
	v_pk_fma_f32 v[46:47], v[48:49], v[204:205], v[46:47] op_sel_hi:[0,1,1]
	v_mul_f32_e32 v49, 0xbfb8aa3b, v207
	v_exp_f32_e32 v49, v49
	s_nop 0
	v_add_f32_e32 v49, 1.0, v49
	v_rcp_f32_e32 v209, v49
	s_nop 0
	v_pk_mul_f32 v[204:205], v[208:209], v[206:207]
	s_nop 0
	v_pk_mul_f32 v[46:47], v[46:47], v[204:205]
	v_cvt_pk_bf16_f32 v204, v44, v45
	v_lshl_add_u64 v[44:45], s[88:89], 0, v[100:101]
	v_add_co_u32_e32 v44, vcc, s7, v44
	v_cvt_pk_bf16_f32 v205, v46, v47
	s_nop 0
	v_addc_co_u32_e32 v45, vcc, 0, v45, vcc
	global_store_dwordx2 v[44:45], v[204:205], off
	v_lshl_add_u64 v[204:205], s[88:89], 0, v[108:109]
	v_add_co_u32_e32 v204, vcc, s3, v204
	v_mov_b64_e32 v[46:47], v[228:229]
	s_nop 0
	v_addc_co_u32_e32 v205, vcc, 0, v205, vcc
	v_mov_b64_e32 v[204:205], v[230:231]
	v_lshl_add_u64 v[100:101], v[100:101], 0, s[4:5]
	v_lshl_add_u64 v[108:109], v[108:109], 0, s[4:5]
	v_lshlrev_b32_e32 v206, 16, v46
	v_and_b32_e32 v207, 0xffff0000, v46
	v_pk_fma_f32 v[40:41], v[48:49], v[206:207], v[40:41] op_sel_hi:[0,1,1]
	v_lshlrev_b32_e32 v208, 16, v204
	v_mul_f32_e32 v46, 0xbfb8aa3b, v208
	v_exp_f32_e32 v46, v46
	v_and_b32_e32 v209, 0xffff0000, v204
	v_lshlrev_b32_e32 v204, 16, v205
	v_mul_f32_e32 v49, 0xbfb8aa3b, v204
	v_add_f32_e32 v46, 1.0, v46
	v_rcp_f32_e32 v210, v46
	v_mul_f32_e32 v46, 0xbfb8aa3b, v209
	v_exp_f32_e32 v46, v46
	v_exp_f32_e32 v49, v49
	v_and_b32_e32 v205, 0xffff0000, v205
	v_add_f32_e32 v46, 1.0, v46
	v_rcp_f32_e32 v211, v46
	v_lshlrev_b32_e32 v46, 16, v47
	v_and_b32_e32 v47, 0xffff0000, v47
	v_add_f32_e32 v49, 1.0, v49
	v_pk_fma_f32 v[42:43], v[48:49], v[46:47], v[42:43] op_sel_hi:[0,1,1]
	v_mul_f32_e32 v46, 0xbfb8aa3b, v205
	v_exp_f32_e32 v46, v46
	v_pk_mul_f32 v[206:207], v[210:211], v[208:209]
	v_add_f32_e32 v46, 1.0, v46
	v_pk_mul_f32 v[40:41], v[40:41], v[206:207]
	v_rcp_f32_e32 v206, v49
	v_rcp_f32_e32 v207, v46
	v_cvt_pk_bf16_f32 v40, v40, v41
	v_pk_mul_f32 v[46:47], v[206:207], v[204:205]
	s_nop 0
	v_pk_mul_f32 v[42:43], v[42:43], v[46:47]
	s_nop 0
	v_cvt_pk_bf16_f32 v41, v42, v43
	v_lshl_add_u64 v[42:43], s[88:89], 0, v[106:107]
	v_add_co_u32_e32 v42, vcc, s3, v42
	global_store_dwordx2 v[44:45], v[40:41], off offset:32
	s_nop 0
	v_addc_co_u32_e32 v43, vcc, 0, v43, vcc
	v_mov_b64_e32 v[40:41], v[232:233]
	v_lshl_add_u64 v[106:107], v[106:107], 0, s[4:5]
	v_mov_b64_e32 v[42:43], v[234:235]
	v_lshlrev_b32_e32 v46, 16, v40
	v_and_b32_e32 v47, 0xffff0000, v40
	v_lshlrev_b32_e32 v204, 16, v42
	v_mul_f32_e32 v40, 0xbfb8aa3b, v204
	v_exp_f32_e32 v40, v40
	v_and_b32_e32 v205, 0xffff0000, v42
	v_pk_fma_f32 v[36:37], v[48:49], v[46:47], v[36:37] op_sel_hi:[0,1,1]
	v_lshlrev_b32_e32 v42, 16, v43
	v_add_f32_e32 v40, 1.0, v40
	v_rcp_f32_e32 v206, v40
	v_mul_f32_e32 v40, 0xbfb8aa3b, v205
	v_exp_f32_e32 v40, v40
	v_and_b32_e32 v43, 0xffff0000, v43
	v_add_f32_e32 v40, 1.0, v40
	v_rcp_f32_e32 v207, v40
	v_lshlrev_b32_e32 v40, 16, v41
	v_and_b32_e32 v41, 0xffff0000, v41
	v_pk_fma_f32 v[38:39], v[48:49], v[40:41], v[38:39] op_sel_hi:[0,1,1]
	v_pk_mul_f32 v[46:47], v[206:207], v[204:205]
	v_mul_f32_e32 v40, 0xbfb8aa3b, v43
	v_pk_mul_f32 v[36:37], v[36:37], v[46:47]
	v_mul_f32_e32 v46, 0xbfb8aa3b, v42
	v_exp_f32_e32 v46, v46
	v_exp_f32_e32 v40, v40
	v_cvt_pk_bf16_f32 v36, v36, v37
	v_add_f32_e32 v46, 1.0, v46
	v_add_f32_e32 v40, 1.0, v40
	v_rcp_f32_e32 v46, v46
	v_rcp_f32_e32 v47, v40
	s_nop 0
	v_pk_mul_f32 v[40:41], v[46:47], v[42:43]
	s_nop 0
	v_pk_mul_f32 v[38:39], v[38:39], v[40:41]
	s_nop 0
	v_cvt_pk_bf16_f32 v37, v38, v39
	v_lshl_add_u64 v[38:39], s[88:89], 0, v[104:105]
	v_add_co_u32_e32 v38, vcc, s3, v38
	global_store_dwordx2 v[44:45], v[36:37], off offset:64
	s_nop 0
	v_addc_co_u32_e32 v39, vcc, 0, v39, vcc
	v_mov_b64_e32 v[36:37], v[236:237]
	v_lshl_add_u64 v[104:105], v[104:105], 0, s[4:5]
	v_mov_b64_e32 v[38:39], v[238:239]
	v_lshlrev_b32_e32 v40, 16, v36
	v_and_b32_e32 v41, 0xffff0000, v36
	v_lshlrev_b32_e32 v42, 16, v38
	v_mul_f32_e32 v36, 0xbfb8aa3b, v42
	v_exp_f32_e32 v36, v36
	v_and_b32_e32 v43, 0xffff0000, v38
	v_pk_fma_f32 v[32:33], v[48:49], v[40:41], v[32:33] op_sel_hi:[0,1,1]
	v_lshlrev_b32_e32 v38, 16, v39
	v_add_f32_e32 v36, 1.0, v36
	v_rcp_f32_e32 v46, v36
	v_mul_f32_e32 v36, 0xbfb8aa3b, v43
	v_exp_f32_e32 v36, v36
	v_and_b32_e32 v39, 0xffff0000, v39
	v_add_f32_e32 v36, 1.0, v36
	v_rcp_f32_e32 v47, v36
	v_lshlrev_b32_e32 v36, 16, v37
	v_and_b32_e32 v37, 0xffff0000, v37
	v_pk_fma_f32 v[34:35], v[48:49], v[36:37], v[34:35] op_sel_hi:[0,1,1]
	v_pk_mul_f32 v[40:41], v[46:47], v[42:43]
	v_mul_f32_e32 v36, 0xbfb8aa3b, v39
	v_pk_mul_f32 v[32:33], v[32:33], v[40:41]
	v_mul_f32_e32 v40, 0xbfb8aa3b, v38
	v_exp_f32_e32 v40, v40
	v_exp_f32_e32 v36, v36
	v_cvt_pk_bf16_f32 v32, v32, v33
	v_add_f32_e32 v40, 1.0, v40
	v_add_f32_e32 v36, 1.0, v36
	v_rcp_f32_e32 v40, v40
	v_rcp_f32_e32 v41, v36
	s_nop 0
	v_pk_mul_f32 v[36:37], v[40:41], v[38:39]
	s_nop 0
	v_pk_mul_f32 v[34:35], v[34:35], v[36:37]
	s_nop 0
	v_cvt_pk_bf16_f32 v33, v34, v35
	global_store_dwordx2 v[44:45], v[32:33], off offset:96
	s_cbranch_scc0 .LBB0_524
; #define MFMA16(a, b, c) __builtin_amdgcn_mfma_f32_16x16x32_bf16((a), (b), (c), 0, 0, 0)
; __device__ __forceinline__ void ssd_s3_unit(const Params& p, int unit, unsigned char* ldsb) {
;     ...
;         bf16x8 hf[16];
; #pragma unroll
;         for (int i = 0; i < 16; ++i) hf[i] = ld8g(hp + (size_t)((i & 3) * 16 + l15) * 128 + (i >> 2) * 32 + quad * 8);
;         __builtin_amdgcn_sched_barrier(0);
; #pragma unroll
;         for (int ks = 0; ks < 4; ++ks) {
;             const bf16x8 bfr = *(const bf16x8*)(Cs + lrow * 136 + ks * 32 + quad * 8);
; #pragma unroll
;             for (int mt = 0; mt < 4; ++mt) acc[mt] = MFMA16(hf[ks * 4 + mt], bfr, acc[mt]);
;         }
;         const float el = __expf(csl);
; #pragma unroll
;         for (int mt = 0; mt < 4; ++mt) { acc[mt][0] *= el; acc[mt][1] *= el; acc[mt][2] *= el; acc[mt][3] *= el; }
; #pragma unroll
;         for (int kk = 0; kk < 4; ++kk) {
;             if (2 * kk <= wave) {
;                 float mv[8];
; #pragma unroll
;                 for (int j = 0; j < 8; ++j) {
;                     const int tile = 2 * kk + (j >> 2), s = tile * 16 + quad * 4 + (j & 3);
;                     const float cbv = cbt[tile][j & 3];
;                     const float e = __expf(csl - csb[hh * 128 + s]) * dtb[hh * 128 + s];
;                     mv[j] = (s <= lrow) ? cbv * e : 0.f;
;                 }
.LBB0_543:
	s_barrier
	v_add_u32_e32 v52, 0, v87
	ds_read_b32 v203, v52
	v_add_u32_e32 v52, v85, v176
	ds_read_b128 v[248:251], v52
	s_andn2_b64 vcc, exec, s[0:1]
	ds_read_b128 v[32:35], v253
	ds_read_b128 v[36:39], v253 offset:4096
	ds_read_b128 v[224:227], v253 offset:8192
	ds_read_b128 v[40:43], v253 offset:12288
	ds_read_b128 v[44:47], v253 offset:13312
	ds_read_b128 v[48:51], v253 offset:1024
	ds_read_b128 v[208:211], v253 offset:5120
	ds_read_b128 v[216:219], v253 offset:9216
	ds_read_b128 v[212:215], v253 offset:6144
	ds_read_b128 v[232:235], v253 offset:10240
	ds_read_b128 v[204:207], v253 offset:2048
	ds_read_b128 v[240:243], v253 offset:14336
	s_waitcnt lgkmcnt(11)
	v_mfma_f32_16x16x32_bf16 v[32:35], v[32:35], v[248:251], 0
	s_waitcnt lgkmcnt(10)
	v_mfma_f32_16x16x32_bf16 v[36:39], v[36:39], v[248:251], 0
	s_waitcnt lgkmcnt(9)
	v_mfma_f32_16x16x32_bf16 v[224:227], v[224:227], v[248:251], 0
	s_waitcnt lgkmcnt(8)
	v_mfma_f32_16x16x32_bf16 v[40:43], v[40:43], v[248:251], 0
	ds_read_b128 v[248:251], v52 offset:64
	ds_read_b128 v[228:231], v253 offset:7168
	ds_read_b128 v[236:239], v253 offset:11264
	ds_read_b128 v[220:223], v253 offset:3072
	ds_read_b128 v[244:247], v253 offset:15360
	s_waitcnt lgkmcnt(4)
	v_mfma_f32_16x16x32_bf16 v[40:43], v[44:47], v[248:251], v[40:43]
	ds_read_b128 v[44:47], v52 offset:128
	s_waitcnt lgkmcnt(12)
	v_mfma_f32_16x16x32_bf16 v[32:35], v[48:51], v[248:251], v[32:35]
	s_waitcnt lgkmcnt(11)
	v_mfma_f32_16x16x32_bf16 v[36:39], v[208:211], v[248:251], v[36:39]
	ds_read_b128 v[208:211], v52 offset:192
	s_waitcnt lgkmcnt(11)
	v_mfma_f32_16x16x32_bf16 v[48:51], v[216:219], v[248:251], v[224:227]
	s_waitcnt lgkmcnt(1)
	v_mfma_f32_16x16x32_bf16 v[36:39], v[212:215], v[44:47], v[36:39]
	s_waitcnt lgkmcnt(9)
	v_mfma_f32_16x16x32_bf16 v[48:51], v[232:235], v[44:47], v[48:51]
	s_waitcnt lgkmcnt(8)
	v_mfma_f32_16x16x32_bf16 v[32:35], v[204:207], v[44:47], v[32:35]
	s_waitcnt lgkmcnt(7)
	v_mfma_f32_16x16x32_bf16 v[204:207], v[240:243], v[44:47], v[40:43]
	s_waitcnt lgkmcnt(0)
	v_mfma_f32_16x16x32_bf16 v[40:43], v[228:231], v[208:211], v[36:39]
	s_waitcnt lgkmcnt(4)
	v_mfma_f32_16x16x32_bf16 v[36:39], v[236:239], v[208:211], v[48:51]
	s_nop 2
	v_mul_f32_e32 v48, 0x3fb8aa3b, v203
	v_add_u32_e32 v50, 0, v89
	v_exp_f32_e32 v52, v48
	v_add_u32_e32 v48, 0x22000, v50
	ds_read_b64 v[48:49], v48
	v_add_u32_e32 v50, 0x22800, v50
	ds_read_b64 v[50:51], v50
	s_waitcnt lgkmcnt(5)
	v_mfma_f32_16x16x32_bf16 v[44:47], v[220:223], v[208:211], v[32:35]
	v_mul_f32_e64 v42, v52, v42
	v_mul_f32_e64 v43, v52, v43
	s_waitcnt lgkmcnt(1)
	v_sub_f32_e32 v48, v203, v48
	v_mul_f32_e32 v48, 0x3fb8aa3b, v48
	v_exp_f32_e32 v48, v48
	v_mfma_f32_16x16x32_bf16 v[32:35], v[244:247], v[208:211], v[204:207]
	s_add_i32 s10, s32, 0x8800
	s_mov_b32 m0, s10
	s_nop 0
	global_load_lds_dwordx4 v[254:255], off
	s_add_i32 s10, s10, 0x3c0
	s_mov_b32 m0, s10
	s_nop 0
	global_load_lds_dwordx4 v[254:255], off offset:64
	s_xor_b32 s32, s32, 0x4000
	s_mov_b64 s[98:99], 0x16800000
	s_mov_b64 s[100:101], 0x4301000
	v_lshl_add_u64 v[214:215], s[88:89], 0, v[110:111]
	v_lshl_add_u64 v[216:217], s[88:89], 0, v[102:103]
	v_lshl_add_u64 v[218:219], s[88:89], 0, v[108:109]
	v_lshl_add_u64 v[220:221], s[88:89], 0, v[106:107]
	v_lshl_add_u64 v[222:223], s[88:89], 0, v[104:105]
	v_lshl_add_u64 v[214:215], v[214:215], 0, s[98:99]
	v_lshl_add_u64 v[216:217], v[216:217], 0, s[100:101]
	v_lshl_add_u64 v[218:219], v[218:219], 0, s[100:101]
	v_lshl_add_u64 v[220:221], v[220:221], 0, s[100:101]
	v_lshl_add_u64 v[222:223], v[222:223], 0, s[100:101]
	s_add_u32 s10, s96, s90
	s_addc_u32 s11, s6, s91
	global_load_dwordx2 v[224:225], v[214:215], off
	global_load_dwordx2 v[226:227], v[216:217], off offset:2048
	global_load_dword v240, v53, s[10:11]
	global_load_dwordx2 v[228:229], v[214:215], off offset:32
	global_load_dwordx2 v[230:231], v[218:219], off offset:2048
	global_load_dwordx2 v[232:233], v[214:215], off offset:64
	global_load_dwordx2 v[234:235], v[220:221], off offset:2048
	global_load_dwordx2 v[236:237], v[214:215], off offset:96
	global_load_dwordx2 v[238:239], v[222:223], off offset:2048
	v_mul_f32_e64 v46, v52, v46
	v_mul_f32_e64 v47, v52, v47
	v_pk_mul_f32 v[44:45], v[52:53], v[44:45] op_sel_hi:[0,1]
	s_waitcnt lgkmcnt(0)
	v_mul_f32_e32 v48, v50, v48
	v_mul_f32_e32 v48, v0, v48
	v_cndmask_b32_e64 v208, v48, 0, s[20:21]
	v_sub_f32_e32 v48, v203, v49
	v_mul_f32_e32 v48, 0x3fb8aa3b, v48
	v_exp_f32_e32 v48, v48
	v_add_u32_e32 v49, 0, v91
	v_add_u32_e32 v50, 0x22800, v49
	v_pk_mul_f32 v[40:41], v[52:53], v[40:41] op_sel_hi:[0,1]
	v_mul_f32_e32 v48, v51, v48
	v_mul_f32_e32 v48, v1, v48
	v_cndmask_b32_e64 v209, 0, v48, s[22:23]
	v_add_u32_e32 v48, 0x22000, v49
	v_add_u32_e32 v49, 0, v182
	ds_read_b32 v48, v48
	ds_read_b32 v49, v49
	ds_read_b64 v[50:51], v50
	v_pk_mul_f32 v[38:39], v[52:53], v[38:39] op_sel_hi:[0,1]
	v_pk_mul_f32 v[36:37], v[52:53], v[36:37] op_sel_hi:[0,1]
	s_waitcnt lgkmcnt(2)
	v_sub_f32_e32 v48, v203, v48
	s_waitcnt lgkmcnt(1)
	v_sub_f32_e32 v49, v203, v49
	v_mul_f32_e32 v48, 0x3fb8aa3b, v48
	v_mul_f32_e32 v49, 0x3fb8aa3b, v49
	v_exp_f32_e32 v48, v48
	v_exp_f32_e32 v49, v49
	v_pk_mul_f32 v[34:35], v[52:53], v[34:35] op_sel_hi:[0,1]
	v_pk_mul_f32 v[32:33], v[52:53], v[32:33] op_sel_hi:[0,1]
	s_waitcnt lgkmcnt(0)
	v_pk_mul_f32 v[48:49], v[50:51], v[48:49]
	s_nop 0
	v_pk_mul_f32 v[50:51], v[2:3], v[48:49]
	v_add_u32_e32 v49, 0, v93
	v_add_u32_e32 v48, 0x22000, v49
	v_add_u32_e32 v204, 0x22800, v49
	v_add_u32_e32 v49, 0, v183
	ds_read_b32 v48, v48
	ds_read_b32 v49, v49
	ds_read_b64 v[204:205], v204
	s_waitcnt lgkmcnt(2)
	v_sub_f32_e32 v48, v203, v48
	s_waitcnt lgkmcnt(1)
; __device__ __forceinline__ unsigned pk2(float lo, float hi) { f32x2_t v = {lo, hi}; bf16x2_t b = __builtin_convertvector(v, bf16x2_t); return __builtin_bit_cast(unsigned, b); }
; #define MFMA16(a, b, c) __builtin_amdgcn_mfma_f32_16x16x32_bf16((a), (b), (c), 0, 0, 0)
; __device__ __forceinline__ void ssd_s3_unit(const Params& p, int unit, unsigned char* ldsb) {
;     ...
; #pragma unroll
;         for (int kk = 0; kk < 4; ++kk) {
;             if (2 * kk <= wave) {
;                 float mv[8];
; #pragma unroll
;                 for (int j = 0; j < 8; ++j) {
;                     const int tile = 2 * kk + (j >> 2), s = tile * 16 + quad * 4 + (j & 3);
;                     const float cbv = cbt[tile][j & 3];
;                     const float e = __expf(csl - csb[hh * 128 + s]) * dtb[hh * 128 + s];
;                     mv[j] = (s <= lrow) ? cbv * e : 0.f;
;                 }
;                 uint4 pu; pu.x = pk2(mv[0], mv[1]); pu.y = pk2(mv[2], mv[3]); pu.z = pk2(mv[4], mv[5]); pu.w = pk2(mv[6], mv[7]);
;                 const bf16x8 pf = __builtin_bit_cast(bf16x8, pu);
; #pragma unroll
;                 for (int mt = 0; mt < 4; ++mt) {
;                     const bfu* xp = XT + (mt * 16 + l15) * 136 + 32 * kk + quad * 4;
;                     acc[mt] = MFMA16(mk8(*(const uint2*)xp, *(const uint2*)(xp + 16)), pf, acc[mt]);
;                 }
;             }
;         }
	v_sub_f32_e32 v49, v203, v49
	v_mul_f32_e32 v48, 0x3fb8aa3b, v48
	v_mul_f32_e32 v49, 0x3fb8aa3b, v49
	v_exp_f32_e32 v48, v48
	v_exp_f32_e32 v49, v49
	s_waitcnt lgkmcnt(0)
	v_pk_mul_f32 v[48:49], v[204:205], v[48:49]
	s_nop 0
	v_pk_mul_f32 v[204:205], v[8:9], v[48:49]
	v_add_u32_e32 v49, 0, v95
	v_add_u32_e32 v48, 0x22000, v49
	v_add_u32_e32 v206, 0x22800, v49
	v_add_u32_e32 v49, 0, v184
	ds_read_b32 v48, v48
	ds_read_b32 v49, v49
	ds_read_b64 v[206:207], v206
	s_waitcnt lgkmcnt(2)
	v_sub_f32_e32 v48, v203, v48
	s_waitcnt lgkmcnt(1)
	v_sub_f32_e32 v49, v203, v49
	v_mul_f32_e32 v48, 0x3fb8aa3b, v48
	v_mul_f32_e32 v49, 0x3fb8aa3b, v49
	v_exp_f32_e32 v48, v48
	v_exp_f32_e32 v49, v49
	s_waitcnt lgkmcnt(0)
	v_pk_mul_f32 v[48:49], v[206:207], v[48:49]
	s_nop 0
	v_pk_mul_f32 v[206:207], v[10:11], v[48:49]
	v_cvt_pk_bf16_f32 v49, v50, v51
	v_cndmask_b32_e64 v50, v49, 0, s[26:27]
	v_lshrrev_b32_e32 v49, 16, v49
	v_cndmask_b32_e64 v49, v49, 0, s[24:25]
	v_perm_b32 v49, v49, v50, s33
	v_cvt_pk_bf16_f32 v50, v204, v205
	v_cndmask_b32_e64 v51, v50, 0, s[30:31]
	v_lshrrev_b32_e32 v50, 16, v50
	v_cndmask_b32_e64 v50, v50, 0, s[28:29]
	v_perm_b32 v50, v50, v51, s33
	v_cvt_pk_bf16_f32 v51, v206, v207
	v_cndmask_b32_e64 v204, v51, 0, s[36:37]
	v_lshrrev_b32_e32 v51, 16, v51
	v_cndmask_b32_e64 v51, v51, 0, s[34:35]
	v_perm_b32 v51, v51, v204, s33
	v_add_u32_e32 v204, 0, v200
	v_add_u32_e32 v205, 0x11000, v204
	ds_read_b64 v[206:207], v205
	v_add_u32_e32 v205, 0x11020, v204
	v_cvt_pk_bf16_f32 v48, v208, v209
	ds_read_b64 v[208:209], v205
	v_add_u32_e32 v205, 0, v201
	s_waitcnt lgkmcnt(0)
	v_mfma_f32_16x16x32_bf16 v[44:47], v[206:209], v[48:51], v[44:47]
	v_add_u32_e32 v206, 0x11000, v205
	v_add_u32_e32 v208, 0x11020, v205
	ds_read_b64 v[206:207], v206
	ds_read_b64 v[208:209], v208
	s_waitcnt lgkmcnt(0)
	v_mfma_f32_16x16x32_bf16 v[40:43], v[206:209], v[48:51], v[40:43]
	v_add_u32_e32 v206, 0, v202
	ds_read2_b64 v[208:211], v206 offset1:4
	v_add_u32_e32 v207, 0x1000, v206
	s_waitcnt lgkmcnt(0)
	v_mfma_f32_16x16x32_bf16 v[36:39], v[208:211], v[48:51], v[36:39]
	ds_read2_b64 v[208:211], v207 offset0:32 offset1:36
	s_waitcnt lgkmcnt(0)
	v_mfma_f32_16x16x32_bf16 v[32:35], v[208:211], v[48:51], v[32:35]
	s_cbranch_vccnz .LBB0_546
	v_add_u32_e32 v49, 0, v97
	v_add_u32_e32 v48, 0x22000, v49
	v_add_u32_e32 v50, 0x22800, v49
	v_add_u32_e32 v49, 0, v185
	ds_read_b32 v48, v48
	ds_read_b32 v49, v49
	ds_read_b64 v[50:51], v50
	s_waitcnt lgkmcnt(2)
	v_sub_f32_e32 v48, v203, v48
	s_waitcnt lgkmcnt(1)
	v_sub_f32_e32 v49, v203, v49
	v_mul_f32_e32 v48, 0x3fb8aa3b, v48
	v_mul_f32_e32 v49, 0x3fb8aa3b, v49
	v_exp_f32_e32 v48, v48
	v_exp_f32_e32 v49, v49
	s_waitcnt lgkmcnt(0)
	v_pk_mul_f32 v[48:49], v[50:51], v[48:49]
	v_add_u32_e32 v51, 0, v163
	v_add_u32_e32 v50, 0x22000, v51
	v_add_u32_e32 v52, 0x22800, v51
	v_add_u32_e32 v51, 0, v186
	ds_read_b32 v50, v50
	ds_read_b32 v51, v51
	ds_read_b64 v[208:209], v52
	v_add_u32_e32 v52, 0, v164
	v_pk_mul_f32 v[48:49], v[12:13], v[48:49]
	s_waitcnt lgkmcnt(2)
	v_sub_f32_e32 v50, v203, v50
	s_waitcnt lgkmcnt(1)
	v_sub_f32_e32 v51, v203, v51
	v_mul_f32_e32 v50, 0x3fb8aa3b, v50
	v_mul_f32_e32 v51, 0x3fb8aa3b, v51
	v_exp_f32_e32 v50, v50
	v_exp_f32_e32 v51, v51
	v_cvt_pk_bf16_f32 v48, v48, v49
	v_cndmask_b32_e64 v49, v48, 0, s[40:41]
	v_lshrrev_b32_e32 v48, 16, v48
	s_waitcnt lgkmcnt(0)
	v_pk_mul_f32 v[50:51], v[208:209], v[50:51]
	v_add_u32_e32 v208, 0x22000, v52
	v_add_u32_e32 v209, 0, v187
	ds_read_b32 v208, v208
	ds_read_b32 v209, v209
	v_add_u32_e32 v52, 0x22800, v52
	ds_read_b64 v[210:211], v52
	v_add_u32_e32 v52, 0, v165
	s_waitcnt lgkmcnt(2)
	v_sub_f32_e32 v208, v203, v208
	s_waitcnt lgkmcnt(1)
	v_sub_f32_e32 v209, v203, v209
	v_mul_f32_e32 v208, 0x3fb8aa3b, v208
	v_mul_f32_e32 v209, 0x3fb8aa3b, v209
	v_exp_f32_e32 v208, v208
	v_exp_f32_e32 v209, v209
	v_pk_mul_f32 v[50:51], v[14:15], v[50:51]
	v_cndmask_b32_e64 v48, v48, 0, s[38:39]
	v_perm_b32 v48, v48, v49, s33
	s_waitcnt lgkmcnt(0)
	v_pk_mul_f32 v[208:209], v[210:211], v[208:209]
	v_add_u32_e32 v210, 0x22000, v52
	v_add_u32_e32 v211, 0, v188
	ds_read_b32 v210, v210
	ds_read_b32 v211, v211
	v_add_u32_e32 v52, 0x22800, v52
	ds_read_b64 v[212:213], v52
	v_cvt_pk_bf16_f32 v49, v50, v51
	s_waitcnt lgkmcnt(2)
	v_sub_f32_e32 v210, v203, v210
	s_waitcnt lgkmcnt(1)
	v_sub_f32_e32 v211, v203, v211
	v_mul_f32_e32 v210, 0x3fb8aa3b, v210
	v_mul_f32_e32 v211, 0x3fb8aa3b, v211
	v_exp_f32_e32 v210, v210
	v_exp_f32_e32 v211, v211
	v_cndmask_b32_e64 v50, v49, 0, s[44:45]
	v_lshrrev_b32_e32 v49, 16, v49
	v_pk_mul_f32 v[208:209], v[4:5], v[208:209]
	v_cndmask_b32_e64 v49, v49, 0, s[42:43]
	v_perm_b32 v49, v49, v50, s33
	v_cvt_pk_bf16_f32 v50, v208, v209
	s_waitcnt lgkmcnt(0)
	v_pk_mul_f32 v[210:211], v[212:213], v[210:211]
	v_cndmask_b32_e64 v51, v50, 0, s[48:49]
	v_lshrrev_b32_e32 v50, 16, v50
	v_pk_mul_f32 v[210:211], v[6:7], v[210:211]
	v_cndmask_b32_e64 v50, v50, 0, s[46:47]
	v_perm_b32 v50, v50, v51, s33
	v_cvt_pk_bf16_f32 v51, v210, v211
	v_cndmask_b32_e64 v52, v51, 0, s[52:53]
	v_lshrrev_b32_e32 v51, 16, v51
	v_cndmask_b32_e64 v51, v51, 0, s[50:51]
	v_perm_b32 v51, v51, v52, s33
	v_add_u32_e32 v52, 0x11040, v204
	ds_read_b64 v[208:209], v52
	v_add_u32_e32 v52, 0x11060, v204
	ds_read_b64 v[210:211], v52
	v_add_u32_e32 v52, 0x11040, v205
	s_waitcnt lgkmcnt(0)
	v_mfma_f32_16x16x32_bf16 v[44:47], v[208:211], v[48:51], v[44:47]
	ds_read_b64 v[208:209], v52
	v_add_u32_e32 v52, 0x11060, v205
	ds_read_b64 v[210:211], v52
	s_waitcnt lgkmcnt(0)
	v_mfma_f32_16x16x32_bf16 v[40:43], v[208:211], v[48:51], v[40:43]
	ds_read2_b64 v[208:211], v206 offset0:8 offset1:12
	s_waitcnt lgkmcnt(0)
	v_mfma_f32_16x16x32_bf16 v[36:39], v[208:211], v[48:51], v[36:39]
	ds_read2_b64 v[208:211], v207 offset0:40 offset1:44
	s_waitcnt lgkmcnt(0)
	v_mfma_f32_16x16x32_bf16 v[32:35], v[208:211], v[48:51], v[32:35]
	s_andn2_b64 vcc, exec, s[94:95]
	s_cbranch_vccz .LBB0_547
